# speedup vs baseline: 1.0234x; 1.0234x over previous
; #define ATT_DMA(t, b) do { \
;         _Pragma("unroll") for (int i_ = 0; i_ < 2; ++i_) glds16(Kg + (size_t)(t) * 64 * ZP + offK[i_], lds + (b) * BUF + (i_ * 8 + wid) * 1024); \
;         _Pragma("unroll") for (int i_ = 0; i_ < 2; ++i_) glds16(Vg + (size_t)(t) * 64 + offV[i_], lds + (b) * BUF + KBYTES + (i_ * 8 + wid) * 1024); } while (0)
; __device__ __forceinline__ void attn_phase(LAS unsigned char* lds, const bf16_t* Z, const bf16_t* VT, bf16_t* Y, const float* subln, float lam, float lam_init, float M0, unsigned* ctr, LAS int* s_unit, int wid_s_) {
;     ...
;         const int U = *s_unit;
;         if (U >= 1024) break;
;         const int h = 7 - (U >> 7), qb = U & 127, q0 = qb * 128, qw = q0 + rg * 32;
;         const float m2 = exp2f(-(float)(h + 1)) * LOG2E;
;         const int W = (int)(150.f / m2) + 1;
;         const int tlo = max(0, q0 - W) >> 6, thi = min(S - 1, q0 + 127 + W) >> 6;
;         const int wlo = max(0, qw - W) >> 6, whi = min(S - 1, qw + 31 + W) >> 6;
;         const bf16_t* Kg = Z + 2048 + h * 128; const bf16_t* Vg = VT + (size_t)h * 128 * S;
;         bf16x8 qf[4];
;         { const bf16_t* qp = Z + (size_t)(qw + rr) * ZP + 1024 + h * 128 + jm * 64 + hh * 8;
; #pragma unroll
;           for (int t4 = 0; t4 < 4; ++t4) qf[t4] = *(const bf16x8*)(qp + t4 * 16); }
;         f32x16 O[4];
; #pragma unroll
;         for (int cb = 0; cb < 4; ++cb)
; #pragma unroll
;             for (int r = 0; r < 16; ++r) O[cb][r] = 0.f;
;         float ls = 0.f;
;     ...
;         const int Tlo = tlo >> 1, Thi = thi >> 1;
;         ATT_DMA(2 * Tlo, 0); ATT_DMA(2 * Tlo + 1, 1);
.LBB0_1294:
	s_or_b64 exec, exec, s[2:3]
	s_waitcnt lgkmcnt(0)
	s_barrier
	ds_read_b32 v0, v97 offset:8
	s_movk_i32 s2, 0x3ff
	s_waitcnt lgkmcnt(0)
	v_cmp_lt_i32_e32 vcc, s2, v0
	v_readfirstlane_b32 s15, v0
	s_mov_b64 s[2:3], -1
	s_cbranch_vccnz .LBB0_1291
	s_ashr_i32 s2, s15, 7
	s_sub_i32 s3, 8, s2
	v_cvt_f32_u32_e32 v0, s3
	s_sub_i32 s26, 7, s2
	s_lshl_b32 s2, s15, 7
	s_and_b32 s16, s2, 0x3f80
	s_mov_b32 s2, 0x42fc0000
	v_cmp_lt_f32_e32 vcc, s2, v0
	v_mov_b32_e32 v1, 0x42800000
	s_add_i32 s40, s16, s25
	v_cndmask_b32_e32 v1, 0, v1, vcc
	v_sub_f32_e32 v0, v1, v0
	v_exp_f32_e32 v0, v0
	s_and_b64 s[2:3], vcc, exec
	s_cselect_b32 s2, 0xffffffc0, 0
	s_mov_b32 s15, 0x42fc0000
	v_ldexp_f32 v0, v0, s2
	v_mul_f32_e32 v171, 0x3fb8aa3b, v0
	v_div_scale_f32 v0, s[2:3], v171, v171, s15
	v_rcp_f32_e32 v1, v0
	s_lshl_b32 s41, s26, 7
	s_mov_b32 m0, s37
	v_mov_b32_e32 v15, 0
	v_fma_f32 v2, -v0, v1, 1.0
	v_fmac_f32_e32 v1, v2, v1
	v_div_scale_f32 v2, vcc, s15, v171, s15
	v_mul_f32_e32 v3, v2, v1
	v_fma_f32 v4, -v0, v3, v2
	v_fmac_f32_e32 v3, v4, v1
	v_fma_f32 v0, -v0, v3, v2
	v_div_fmas_f32 v0, v0, v1, v3
	v_div_fixup_f32 v0, v0, v171, s15
	v_cvt_i32_f32_e32 v0, v0
	v_or_b32_e32 v2, s40, v203
	s_mov_b32 s15, s27
	v_mov_b32_e32 v14, 0
	v_readfirstlane_b32 s17, v0
	s_add_i32 s17, s17, 1
	s_add_i32 s2, s17, s16
	v_mov_b64_e32 v[0:1], s[78:79]
	s_add_i32 s51, s2, 0x7f
	s_lshl_b64 s[2:3], s[26:27], 22
	v_mad_i64_i32 v[0:1], s[48:49], v2, s33, v[0:1]
	s_lshl_b32 s26, s26, 8
	s_sub_i32 s50, s16, s17
	v_lshl_add_u64 v[0:1], v[0:1], 0, s[26:27]
	v_lshl_add_u64 v[0:1], v[0:1], 0, s[14:15]
	s_max_i32 s15, s50, 0
	s_add_u32 s50, s22, s26
	s_addc_u32 s78, s23, 0
	s_lshr_b32 s15, s15, 7
	s_lshl_b32 s26, s15, 1
	s_mul_i32 s86, s15, 0x140000
	s_mul_hi_u32 s49, s26, 0xa0000
	s_add_u32 s48, s50, s86
	v_lshl_add_u64 v[0:1], v[0:1], 0, v[96:97]
	s_addc_u32 s49, s78, s49
	flat_load_dwordx4 v[98:101], v[0:1] offset:2048
	flat_load_dwordx4 v[102:105], v[0:1] offset:2080
	flat_load_dwordx4 v[106:109], v[0:1] offset:2112
	flat_load_dwordx4 v[110:113], v[0:1] offset:2144
	v_lshl_add_u64 v[0:1], s[48:49], 0, v[168:169]
	global_load_lds_dwordx4 v[0:1], off
	v_lshl_add_u64 v[0:1], s[48:49], 0, v[166:167]
	s_add_i32 m0, s37, 0x2000
	v_readlane_b32 s48, v255, 52
	v_readlane_b32 s49, v255, 53
	s_add_u32 s48, s48, s2
	s_addc_u32 s49, s49, s3
	s_lshl_b32 s87, s15, 8
	s_add_u32 s48, s48, s87
	s_addc_u32 s49, s49, 0
	global_load_lds_dwordx4 v[0:1], off
	v_lshl_add_u64 v[0:1], v[156:157], 1, s[48:49]
	s_add_i32 m0, s37, 0x4000
	v_lshl_add_u64 v[2:3], v[158:159], 1, s[48:49]
	s_or_b32 s48, s26, 1
	global_load_lds_dwordx4 v[0:1], off
	s_add_i32 m0, s37, 0x6000
	s_min_i32 s51, s51, 0x3fff
	s_mul_hi_u32 s49, s48, 0xa0000
	s_mul_i32 s48, s48, 0xa0000
	s_add_u32 s48, s50, s48
	s_addc_u32 s49, s78, s49
	global_load_lds_dwordx4 v[2:3], off
	v_lshl_add_u64 v[4:5], s[48:49], 0, v[168:169]
	s_add_i32 m0, s37, 0x8000
	v_lshl_add_u64 v[0:1], v[0:1], 0, s[42:43]
	global_load_lds_dwordx4 v[4:5], off
	v_lshl_add_u64 v[4:5], s[48:49], 0, v[166:167]
	s_add_i32 m0, s37, 0xa000
	s_ashr_i32 s48, s51, 7
	global_load_lds_dwordx4 v[4:5], off
	s_add_i32 m0, s37, 0xc000
	v_mov_b32_e32 v13, 0
	global_load_lds_dwordx4 v[0:1], off
	v_lshl_add_u64 v[0:1], v[2:3], 0, s[42:43]
	s_add_i32 m0, s37, 0xe000
	s_cmp_gt_i32 s15, s48
	global_load_lds_dwordx4 v[0:1], off
	v_mov_b32_e32 v12, 0
	v_mov_b32_e32 v11, 0
	v_mov_b32_e32 v10, 0
	v_mov_b32_e32 v9, 0
	v_mov_b32_e32 v8, 0
	v_mov_b32_e32 v7, 0
	v_mov_b32_e32 v6, 0
	v_mov_b32_e32 v5, 0
	v_mov_b32_e32 v4, 0
	v_mov_b32_e32 v3, 0
	v_mov_b32_e32 v2, 0
	v_mov_b32_e32 v1, 0
	v_mov_b32_e32 v0, 0
	v_mov_b32_e32 v31, 0
	v_mov_b32_e32 v30, 0
	v_mov_b32_e32 v29, 0
	v_mov_b32_e32 v28, 0
	v_mov_b32_e32 v27, 0
	v_mov_b32_e32 v26, 0
	v_mov_b32_e32 v25, 0
	v_mov_b32_e32 v24, 0
	v_mov_b32_e32 v23, 0
	v_mov_b32_e32 v22, 0
	v_mov_b32_e32 v21, 0
	v_mov_b32_e32 v20, 0
	v_mov_b32_e32 v19, 0
	v_mov_b32_e32 v18, 0
	v_mov_b32_e32 v17, 0
	v_mov_b32_e32 v16, 0
	v_mov_b32_e32 v63, 0
	v_mov_b32_e32 v62, 0
	v_mov_b32_e32 v61, 0
	v_mov_b32_e32 v60, 0
	v_mov_b32_e32 v59, 0
	v_mov_b32_e32 v58, 0
	v_mov_b32_e32 v57, 0
	v_mov_b32_e32 v56, 0
	v_mov_b32_e32 v55, 0
	v_mov_b32_e32 v54, 0
	v_mov_b32_e32 v53, 0
	v_mov_b32_e32 v52, 0
	v_mov_b32_e32 v51, 0
	v_mov_b32_e32 v50, 0
	v_mov_b32_e32 v49, 0
	v_mov_b32_e32 v48, 0
	v_mov_b32_e32 v47, 0
	v_mov_b32_e32 v46, 0
	v_mov_b32_e32 v45, 0
	v_mov_b32_e32 v44, 0
	v_mov_b32_e32 v43, 0
	v_mov_b32_e32 v42, 0
	v_mov_b32_e32 v41, 0
	v_mov_b32_e32 v40, 0
	v_mov_b32_e32 v39, 0
	v_mov_b32_e32 v38, 0
	v_mov_b32_e32 v37, 0
	v_mov_b32_e32 v36, 0
	v_mov_b32_e32 v35, 0
	v_mov_b32_e32 v34, 0
	v_mov_b32_e32 v33, 0
	v_mov_b32_e32 v32, 0
	v_mov_b32_e32 v197, 0
	s_cbranch_scc1 .LBB0_1315
	s_sub_i32 s50, s40, s17
	s_max_i32 s51, s50, 0
	s_or_b32 s50, s40, 31
	s_add_i32 s17, s17, s50
	s_min_i32 s17, s17, 0x3fff
	s_lshr_b32 s51, s51, 6
	s_ashr_i32 s84, s17, 6
	s_lshl_b32 s85, s15, 7
	s_add_u32 s2, s87, s2
	s_addc_u32 s3, 0, s3
	s_add_u32 s70, s2, s28
	s_addc_u32 s71, s3, s29
	s_add_u32 s76, s70, 0x1a400180
	s_addc_u32 s77, s71, 0
	s_add_u32 s70, s70, 0x1a400100
	s_addc_u32 s71, s71, 0
	s_lshl_b32 s2, s41, 1
	v_add_u32_e32 v0, s16, v240
	s_mul_hi_u32 s3, s15, 0x140000
	s_add_u32 s2, s2, s86
	v_mov_b32_e32 v32, v97
	v_mov_b32_e32 v33, v97
	v_mov_b32_e32 v46, v97
	v_mov_b32_e32 v47, v97
	v_xor_b32_e32 v172, 0x80000000, v171
	v_subrev_u32_e32 v193, s85, v0
	s_addc_u32 s3, 0, s3
	v_mov_b32_e32 v34, v97
	v_mov_b32_e32 v35, v97
	v_mov_b32_e32 v36, v97
	v_mov_b32_e32 v37, v97
	v_mov_b32_e32 v38, v97
	v_mov_b32_e32 v39, v97
	v_mov_b32_e32 v40, v97
	v_mov_b32_e32 v41, v97
	v_mov_b32_e32 v42, v97
	v_mov_b32_e32 v43, v97
	v_mov_b32_e32 v44, v97
	v_mov_b32_e32 v45, v97
	v_mov_b64_e32 v[62:63], v[46:47]
	v_mov_b64_e32 v[16:17], v[32:33]
	v_mov_b64_e32 v[0:1], v[32:33]
	s_mov_b32 s49, 0
	v_mov_b32_e32 v174, v172
	v_mov_b32_e32 v175, v172
	s_add_u32 s68, s2, s28
	s_addc_u32 s69, s3, s29
	s_add_u32 s72, s68, 0x105e1000
	s_addc_u32 s73, s69, 0
	s_add_u32 s68, s68, 0x10541000
	s_addc_u32 s69, s69, 0
	v_mov_b32_e32 v197, 0
	v_mov_b64_e32 v[60:61], v[44:45]
	v_mov_b64_e32 v[58:59], v[42:43]
	v_mov_b64_e32 v[56:57], v[40:41]
	v_mov_b64_e32 v[54:55], v[38:39]
	v_mov_b64_e32 v[52:53], v[36:37]
	v_mov_b64_e32 v[50:51], v[34:35]
	v_mov_b64_e32 v[48:49], v[32:33]
	v_mov_b64_e32 v[18:19], v[34:35]
	v_mov_b64_e32 v[20:21], v[36:37]
	v_mov_b64_e32 v[22:23], v[38:39]
	v_mov_b64_e32 v[24:25], v[40:41]
	v_mov_b64_e32 v[26:27], v[42:43]
	v_mov_b64_e32 v[28:29], v[44:45]
	v_mov_b64_e32 v[30:31], v[46:47]
	v_mov_b64_e32 v[2:3], v[34:35]
	v_mov_b64_e32 v[4:5], v[36:37]
	v_mov_b64_e32 v[6:7], v[38:39]
	v_mov_b64_e32 v[8:9], v[40:41]
	v_mov_b64_e32 v[10:11], v[42:43]
	v_mov_b64_e32 v[12:13], v[44:45]
	v_mov_b64_e32 v[14:15], v[46:47]
	s_waitcnt vmcnt(0)
	s_branch .LBB0_1299

; #define ATT_DMA(t, b) do { \
;         _Pragma("unroll") for (int i_ = 0; i_ < 2; ++i_) glds16(Kg + (size_t)(t) * 64 * ZP + offK[i_], lds + (b) * BUF + (i_ * 8 + wid) * 1024); \
;         _Pragma("unroll") for (int i_ = 0; i_ < 2; ++i_) glds16(Vg + (size_t)(t) * 64 + offV[i_], lds + (b) * BUF + KBYTES + (i_ * 8 + wid) * 1024); } while (0)
; __device__ __forceinline__ void attn_phase(LAS unsigned char* lds, const bf16_t* Z, const bf16_t* VT, bf16_t* Y, const float* subln, float lam, float lam_init, float M0, unsigned* ctr, LAS int* s_unit, int wid_s_) {
;     ...
;         const int Tlo = tlo >> 1, Thi = thi >> 1;
;         ATT_DMA(2 * Tlo, 0); ATT_DMA(2 * Tlo + 1, 1);
;         for (int T = Tlo; T <= Thi; ++T) {
;             const int b = (T - Tlo) & 1;
;             asm volatile("s_waitcnt vmcnt(0)" ::: "memory");
;             __syncthreads();
;             if (T + 1 <= Thi) { ATT_DMA(2 * T + 2, 2 * (b ^ 1)); ATT_DMA(2 * T + 3, 2 * (b ^ 1) + 1); }
.LBB0_1298:
	s_add_i32 s49, s49, 1
	s_add_i32 s2, s15, s49
	s_addk_i32 s85, 0x80
	s_add_i32 s26, s26, 2
	s_add_i32 s2, s2, -1
	v_add_u32_e32 v193, 0xffffff80, v193
	s_add_u32 s70, s70, s44
	s_addc_u32 s71, s71, s45
	s_add_u32 s76, s76, s44
	s_addc_u32 s77, s77, s45
	s_add_u32 s68, s68, s46
	s_addc_u32 s69, s69, s47
	s_add_u32 s72, s72, s46
	s_addc_u32 s73, s73, s47
	s_cmp_ge_i32 s2, s48
	s_cbranch_scc1 .LBB0_1314
.LBB0_1299:
	s_waitcnt vmcnt(0)
	s_and_b32 s17, s49, 1
	s_lshl_b32 s16, s17, 16
	s_waitcnt lgkmcnt(0)
	s_barrier
	s_bitcmp1_b32 s37, 12
	s_cbranch_scc1 .LBB0_1303
	s_add_i32 s2, s15, s49
	s_cmp_lt_i32 s2, s48
	s_cbranch_scc0 .LBB0_1303
	s_xor_b32 s2, s16, 0x10000
	s_add_i32 s2, s37, s2
	s_mov_b32 m0, s2
	s_nop 0
	global_load_lds_dwordx4 v168, s[68:69]
	s_add_i32 m0, s2, 0x2000
	s_nop 0
	global_load_lds_dwordx4 v166, s[68:69]
	s_add_i32 m0, s2, 0x4000
	s_nop 0
	global_load_lds_dwordx4 v164, s[70:71]
	s_add_i32 m0, s2, 0x6000
	s_nop 0
	global_load_lds_dwordx4 v162, s[70:71]
	s_add_i32 m0, s2, 0x8000
	s_nop 0
	global_load_lds_dwordx4 v168, s[72:73]
	s_add_i32 m0, s2, 0xa000
	s_nop 0
	global_load_lds_dwordx4 v166, s[72:73]
	s_add_i32 m0, s2, 0xc000
	s_nop 0
	global_load_lds_dwordx4 v164, s[76:77]
	s_add_i32 m0, s2, 0xe000
	s_nop 0
	global_load_lds_dwordx4 v162, s[76:77]

; #define ATT_DMA(t, b) do { \
;         _Pragma("unroll") for (int i_ = 0; i_ < 2; ++i_) glds16(Kg + (size_t)(t) * 64 * ZP + offK[i_], lds + (b) * BUF + (i_ * 8 + wid) * 1024); \
;         _Pragma("unroll") for (int i_ = 0; i_ < 2; ++i_) glds16(Vg + (size_t)(t) * 64 + offV[i_], lds + (b) * BUF + KBYTES + (i_ * 8 + wid) * 1024); } while (0)
; __device__ __forceinline__ void attn_phase(LAS unsigned char* lds, const bf16_t* Z, const bf16_t* VT, bf16_t* Y, const float* subln, float lam, float lam_init, float M0, unsigned* ctr, LAS int* s_unit, int wid_s_) {
;     ...
;         const int Tlo = tlo >> 1, Thi = thi >> 1;
;         ATT_DMA(2 * Tlo, 0); ATT_DMA(2 * Tlo + 1, 1);
;         for (int T = Tlo; T <= Thi; ++T) {
;             const int b = (T - Tlo) & 1;
;             asm volatile("s_waitcnt vmcnt(0)" ::: "memory");
;             __syncthreads();
;             if (T + 1 <= Thi) { ATT_DMA(2 * T + 2, 2 * (b ^ 1)); ATT_DMA(2 * T + 3, 2 * (b ^ 1) + 1); }
.LBB0_1309:
	s_bitcmp1_b32 s37, 12
	s_cbranch_scc0 .Ldma_mid_skip
	s_add_i32 s2, s15, s49
	s_cmp_lt_i32 s2, s48
	s_cbranch_scc0 .Ldma_mid_skip
	s_and_b32 s2, s49, 1
	s_lshl_b32 s2, s2, 16
	s_xor_b32 s2, s2, 0x10000
	s_add_i32 s2, s37, s2
	s_mov_b32 m0, s2
	s_nop 0
	global_load_lds_dwordx4 v168, s[68:69]
	s_add_i32 m0, s2, 0x2000
	s_nop 0
	global_load_lds_dwordx4 v166, s[68:69]
	s_add_i32 m0, s2, 0x4000
	s_nop 0
	global_load_lds_dwordx4 v164, s[70:71]
	s_add_i32 m0, s2, 0x6000
	s_nop 0
	global_load_lds_dwordx4 v162, s[70:71]
	s_add_i32 m0, s2, 0x8000
	s_nop 0
	global_load_lds_dwordx4 v168, s[72:73]
	s_add_i32 m0, s2, 0xa000
	s_nop 0
	global_load_lds_dwordx4 v166, s[72:73]
	s_add_i32 m0, s2, 0xc000
	s_nop 0
	global_load_lds_dwordx4 v164, s[76:77]
	s_add_i32 m0, s2, 0xe000
	s_nop 0
	global_load_lds_dwordx4 v162, s[76:77]
